# dil merge loop: data loads issued with the lse loads (one round trip per iteration); GEMM_in row-sum loads prefetched before the peeled tail
# speedup vs baseline: 1.0148x; 1.0005x over previous
; DI f32x16 mfma32(bf16x8 a, bf16x8 b, f32x16 c) { return __builtin_amdgcn_mfma_f32_32x32x16_bf16(a, b, c, 0, 0, 0); }
; #define RAW_BARRIER() do { asm volatile("s_waitcnt lgkmcnt(0)" ::: "memory"); __builtin_amdgcn_s_barrier(); } while (0)
; DI void gemm_tile(const Params& p, const GemmJob& j, int mt, int nt, char* smem) {
;     ...
;   for (int kt = 0; kt < nk; ++kt) {
;     if (kt + 1 < nk) asm volatile("s_waitcnt vmcnt(6)" ::: "memory"); else asm volatile("s_waitcnt vmcnt(0)" ::: "memory");
;     RAW_BARRIER();
;     if (kt + 2 < nk) glds(kt + 2, st2);
;     const char* sb = smem + st * GSTAGE;
; #pragma unroll
;     for (int ks = 0; ks < 2; ++ks) {
;       const int off = ks ? (o0 ^ 32) : o0;
;       bf16x8 wf[2], xf[4];
; #pragma unroll
;       for (int a = 0; a < 2; ++a) wf[a] = *(const bf16x8*)(sb + (64 * wn + 32 * a + r) * 64 + off);
; #pragma unroll
;       for (int b = 0; b < 4; ++b) xf[b] = *(const bf16x8*)(sb + 8192 + (128 * wt + 32 * b + r) * 64 + off);
; #pragma unroll
;       for (int a = 0; a < 2; ++a)
; #pragma unroll
;         for (int b = 0; b < 4; ++b) acc[a][b] = mfma32(wf[a], xf[b], acc[a][b]);
;     }
;     st = (st == 2) ? 0 : st + 1; st2 = (st2 == 2) ? 0 : st2 + 1;
;   }
;   __syncthreads();
;   if (j.epi == E_SEG) {
;     const float* sp = p.ssqp + (size_t)(t0 + tid) * 8;
;     const f32x4 s0 = *(const f32x4*)sp, s1 = *(const f32x4*)(sp + 4);
;     rstd_s[tid] = rsqrtf(((s0[0] + s0[1]) + (s0[2] + s0[3]) + (s1[0] + s1[1]) + (s1[2] + s1[3])) * (1.f / 1024.f) + 1e-6f);
;     __syncthreads();
.LBB0_108:
	v_readlane_b32 s100, v229, 35
	v_readlane_b32 s101, v229, 36
	v_add_u32_e32 v244, s10, v145
	v_ashrrev_i32_e32 v245, 31, v244
	v_lshlrev_b64 v[244:245], 5, v[244:245]
	s_nop 0
	v_lshl_add_u64 v[244:245], s[100:101], 0, v[244:245]
	global_load_dwordx4 v[236:239], v[244:245], off offset:16
	global_load_dwordx4 v[240:243], v[244:245], off
	s_mul_i32 s6, s11, 0x6000
	s_add_i32 s7, s6, 0
	v_add_u32_e32 v0, s7, v147
	s_waitcnt vmcnt(8)
	v_add_u32_e32 v134, v0, v149
	v_add_u32_e32 v0, v0, v148
	s_waitcnt lgkmcnt(0)
	s_barrier
	ds_read_b128 v[130:133], v134
	ds_read_b128 v[134:137], v134 offset:2048
	ds_read_b128 v[138:141], v0 offset:8192
	ds_read_b128 v[152:155], v0 offset:10240
	ds_read_b128 v[156:159], v0 offset:12288
	ds_read_b128 v[160:163], v0 offset:14336
	s_waitcnt lgkmcnt(0)
	v_mfma_f32_32x32x16_bf16 v[114:129], v[130:133], v[138:141], v[114:129]
	v_add_u32_e32 v0, s7, v150
	s_addk_i32 s6, 0x6000
	s_cmp_lg_u32 s11, 2
	s_cselect_b32 s6, s6, 0
	s_add_i32 s6, s6, 0
	v_readlane_b32 s12, v229, 29
	v_readlane_b32 s18, v229, 35
	v_mfma_f32_32x32x16_bf16 v[82:97], v[130:133], v[152:155], v[82:97]
	v_readlane_b32 s19, v229, 36
	v_readlane_b32 s13, v229, 30
	v_readlane_b32 s14, v229, 31
	v_readlane_b32 s15, v229, 32
	v_readlane_b32 s16, v229, 33
	v_readlane_b32 s17, v229, 34
	v_readlane_b32 s20, v229, 37
	v_mfma_f32_32x32x16_bf16 v[50:65], v[130:133], v[156:159], v[50:65]
	v_readlane_b32 s21, v229, 38
	v_readlane_b32 s22, v229, 39
	v_readlane_b32 s23, v229, 40
	v_readlane_b32 s24, v229, 41
	v_readlane_b32 s25, v229, 42
	v_readlane_b32 s26, v229, 43
	v_readlane_b32 s27, v229, 44
	v_mfma_f32_32x32x16_bf16 v[18:33], v[130:133], v[160:163], v[18:33]
	v_mfma_f32_32x32x16_bf16 v[98:113], v[134:137], v[138:141], v[98:113]
	v_mfma_f32_32x32x16_bf16 v[66:81], v[134:137], v[152:155], v[66:81]
	v_mfma_f32_32x32x16_bf16 v[34:49], v[134:137], v[156:159], v[34:49]
	v_mfma_f32_32x32x16_bf16 v[2:17], v[134:137], v[160:163], v[2:17]
	v_add_u32_e32 v134, v0, v149
	v_add_u32_e32 v0, v0, v148
	ds_read_b128 v[130:133], v134
	ds_read_b128 v[134:137], v134 offset:2048
	ds_read_b128 v[138:141], v0 offset:8192
	ds_read_b128 v[152:155], v0 offset:10240
	ds_read_b128 v[156:159], v0 offset:12288
	ds_read_b128 v[160:163], v0 offset:14336
	v_add_u32_e32 v0, s6, v147
	s_waitcnt vmcnt(0)
	s_waitcnt lgkmcnt(0)
	s_waitcnt lgkmcnt(0)
	v_mfma_f32_32x32x16_bf16 v[114:129], v[130:133], v[138:141], v[114:129]
	s_barrier
	v_mfma_f32_32x32x16_bf16 v[82:97], v[130:133], v[152:155], v[82:97]
	v_mfma_f32_32x32x16_bf16 v[50:65], v[130:133], v[156:159], v[50:65]
	v_mfma_f32_32x32x16_bf16 v[18:33], v[130:133], v[160:163], v[18:33]
	v_mfma_f32_32x32x16_bf16 v[98:113], v[134:137], v[138:141], v[98:113]
	v_mfma_f32_32x32x16_bf16 v[66:81], v[134:137], v[152:155], v[66:81]
	v_mfma_f32_32x32x16_bf16 v[34:49], v[134:137], v[156:159], v[34:49]
	v_mfma_f32_32x32x16_bf16 v[2:17], v[134:137], v[160:163], v[2:17]
	v_add_u32_e32 v134, v0, v149
	v_add_u32_e32 v0, v0, v148
	ds_read_b128 v[130:133], v134
	ds_read_b128 v[134:137], v134 offset:2048
	ds_read_b128 v[138:141], v0 offset:8192
	ds_read_b128 v[152:155], v0 offset:10240
	ds_read_b128 v[156:159], v0 offset:12288
	ds_read_b128 v[160:163], v0 offset:14336
	v_add_u32_e32 v0, s6, v150
	s_mov_b32 s6, 0x800000
	s_waitcnt lgkmcnt(0)
	v_mfma_f32_32x32x16_bf16 v[114:129], v[130:133], v[138:141], v[114:129]
	v_mfma_f32_32x32x16_bf16 v[82:97], v[130:133], v[152:155], v[82:97]
	v_mfma_f32_32x32x16_bf16 v[50:65], v[130:133], v[156:159], v[50:65]
	v_mfma_f32_32x32x16_bf16 v[18:33], v[130:133], v[160:163], v[18:33]
	v_mfma_f32_32x32x16_bf16 v[98:113], v[134:137], v[138:141], v[98:113]
	v_mfma_f32_32x32x16_bf16 v[66:81], v[134:137], v[152:155], v[66:81]
	v_mfma_f32_32x32x16_bf16 v[34:49], v[134:137], v[156:159], v[34:49]
	v_mfma_f32_32x32x16_bf16 v[2:17], v[134:137], v[160:163], v[2:17]
	v_add_u32_e32 v134, v0, v149
	v_add_u32_e32 v0, v0, v148
	ds_read_b128 v[130:133], v134
	ds_read_b128 v[134:137], v134 offset:2048
	ds_read_b128 v[138:141], v0 offset:8192
	ds_read_b128 v[148:151], v0 offset:10240
	ds_read_b128 v[152:155], v0 offset:12288
	ds_read_b128 v[156:159], v0 offset:14336
	s_waitcnt vmcnt(0) lgkmcnt(0)
	s_barrier
	v_mfma_f32_32x32x16_bf16 v[114:129], v[130:133], v[138:141], v[114:129]
	v_mfma_f32_32x32x16_bf16 v[82:97], v[130:133], v[148:151], v[82:97]
	v_mfma_f32_32x32x16_bf16 v[50:65], v[130:133], v[152:155], v[50:65]
	v_mfma_f32_32x32x16_bf16 v[18:33], v[130:133], v[156:159], v[18:33]
	v_add_u32_e32 v130, s10, v145
	v_ashrrev_i32_e32 v131, 31, v130
	v_lshlrev_b64 v[130:131], 5, v[130:131]
	v_mfma_f32_32x32x16_bf16 v[98:113], v[134:137], v[138:141], v[98:113]
	v_mfma_f32_32x32x16_bf16 v[66:81], v[134:137], v[148:151], v[66:81]
	v_mfma_f32_32x32x16_bf16 v[34:49], v[134:137], v[152:155], v[34:49]
	v_mfma_f32_32x32x16_bf16 v[2:17], v[134:137], v[156:159], v[2:17]
	v_lshl_add_u64 v[134:135], s[18:19], 0, v[130:131]
	s_waitcnt vmcnt(0)
	v_mov_b32_e32 v130, v236
	v_mov_b32_e32 v131, v237
	v_mov_b32_e32 v132, v238
	v_mov_b32_e32 v133, v239
	v_mov_b32_e32 v134, v240
	v_mov_b32_e32 v135, v241
	v_mov_b32_e32 v136, v242
	v_mov_b32_e32 v137, v243
	v_mov_b32_e32 v138, v135
	v_mov_b32_e32 v139, v136
	v_mov_b32_e32 v135, v137
	v_pk_add_f32 v[134:135], v[138:139], v[134:135]
	v_mov_b32_e32 v136, v132
	v_mov_b32_e32 v137, v130
	v_mov_b32_e32 v130, v133
	v_pk_add_f32 v[130:131], v[136:137], v[130:131]
	v_add_f32_e32 v0, v134, v135
	v_add_f32_e32 v0, v0, v131
	v_add_f32_e32 v0, v130, v0
	v_fmamk_f32 v0, v0, 0x3a800000, v201
	v_cmp_gt_f32_e32 vcc, s6, v0
	v_mul_f32_e32 v130, 0x4b800000, v0
	s_lshl_b32 s6, s54, 6
	v_cndmask_b32_e32 v0, v0, v130, vcc
	v_rsq_f32_e32 v0, v0
	s_or_b32 s11, s6, s86
	s_mul_i32 s6, s50, 0xfffffe84
	s_add_u32 s6, s64, s6
	v_mul_f32_e32 v130, 0x45800000, v0
	v_cndmask_b32_e32 v0, v0, v130, vcc
	v_lshl_add_u32 v130, v145, 2, 0
	v_add_u32_e32 v130, 0x12000, v130
	s_addc_u32 s7, s65, s96
	ds_write_b32 v130, v0
	s_waitcnt lgkmcnt(0)
	s_barrier
	s_load_dword s31, s[6:7], 0x998
	s_mov_b64 s[6:7], 0
	s_waitcnt lgkmcnt(0)
	s_cmp_gt_i32 s31, 1
	s_cselect_b64 s[94:95], -1, 0
	s_cmp_lt_i32 s31, 2
	s_cbranch_scc1 .LBB0_121
	s_cmp_eq_u32 s31, 2
	s_cbranch_scc1 .LBB0_117
	s_add_i32 s8, s31, -1
	s_and_b32 s9, s8, -2
	s_mov_b32 s33, s11
	s_mov_b32 s6, 2
	s_mov_b32 s58, 1
	s_brev_b32 s36, 1
	s_mov_b32 s38, s9
	s_brev_b32 s37, 1

; DI float bflo(unsigned v) { return __uint_as_float(v << 16); }
; DI float bfhi(unsigned v) { return __uint_as_float(v & 0xffff0000u); }
; DI size_t blk(size_t row, int k, int R) { return ((size_t)(k >> 5) * R + row) * 32 + (k & 31); }
; DI void dil_merge_phase(const Params& p, bool probe = false) {
;     ...
;   for (size_t i = gid; i < (size_t)NTOK * 128; i += gsz) {
;     const int t = (int)(i >> 7), c = (int)(i & 127), head = c >> 3;
;     const int b = t >> 12, sq = t & 4095;
;     size_t rows[3]; float ls[3];
; #pragma unroll
;     for (int gi = 0; gi < 3; ++gi) {
;       const int dlog = 2 * gi, dil = 1 << dlog, L = SEQ >> dlog;
;       rows[gi] = (size_t)b * SEQ + (size_t)(sq & (dil - 1)) * L + (sq >> dlog);
;       ls[gi] = p.lse[((size_t)gi * NTOK + rows[gi]) * 16 + head];
;     }
;     const float mx = fmaxf(ls[0], fmaxf(ls[1], ls[2]));
;     float wg[3]; float den = 0.f;
; #pragma unroll
;     for (int gi = 0; gi < 3; ++gi) { wg[gi] = __expf(ls[gi] - mx); den += wg[gi]; }
;     const float inv = 1.f / den;
;     float acc[8] = {0.f, 0.f, 0.f, 0.f, 0.f, 0.f, 0.f, 0.f};
; #pragma unroll
;     for (int gi = 0; gi < 3; ++gi) {
;       const u32x4 ov = *(const u32x4*)(p.Q + (size_t)gi * NTOK * 1024 + rows[gi] * 1024 + c * 8);
;       const float wq = wg[gi] * inv;
; #pragma unroll
;       for (int e = 0; e < 4; ++e) { acc[2 * e] += wq * bflo(ov[e]); acc[2 * e + 1] += wq * bfhi(ov[e]); }
;     }
;     bf16_t* gp = p.G + blk(t, c * 8, NTOK);
;     const u32x4 gv = *(const u32x4*)gp;
;     u32x4 ov;
.LBB0_865:
	v_lshrrev_b64 v[38:39], 7, v[14:15]
	v_lshlrev_b64 v[2:3], 6, v[38:39]
	v_alignbit_b32 v4, v15, v14, 7
	v_lshl_add_u64 v[2:3], v[18:19], 0, v[2:3]
	v_lshlrev_b32_e32 v0, 3, v14
	v_and_b32_e32 v5, 0x7000, v4
	global_load_dword v6, v[2:3], off
	v_and_b32_e32 v0, 0xc00, v0
	v_bfe_u32 v2, v4, 2, 10
	v_or3_b32 v7, v0, v2, v5
	v_lshlrev_b32_e32 v0, 6, v7
	v_lshl_add_u64 v[2:3], v[20:21], 0, v[0:1]
	v_lshlrev_b32_e32 v0, 1, v14
	global_load_dword v8, v[2:3], off
	v_and_b32_e32 v0, 0xf00, v0
	v_bfe_u32 v2, v4, 4, 8
	v_or3_b32 v10, v0, v2, v5
	v_lshlrev_b32_e32 v0, 6, v10
	v_lshl_add_u64 v[2:3], v[22:23], 0, v[0:1]
	global_load_dword v0, v[2:3], off
	v_lshl_add_u64 v[14:15], v[14:15], 0, s[48:49]
	v_lshlrev_b32_e32 v248, 11, v7
	v_mov_b32_e32 v249, 0
	v_lshl_add_u64 v[250:251], v[26:27], 0, v[248:249]
	global_load_dwordx4 v[236:239], v[250:251], off
	v_lshlrev_b32_e32 v248, 11, v10
	v_lshl_add_u64 v[250:251], v[28:29], 0, v[248:249]
	global_load_dwordx4 v[244:247], v[250:251], off
	v_lshlrev_b64 v[250:251], 11, v[38:39]
	v_lshl_add_u64 v[250:251], v[24:25], 0, v[250:251]
	global_load_dwordx4 v[232:235], v[250:251], off
	v_lshl_add_u64 v[250:251], v[38:39], 0, v[16:17]
	v_lshlrev_b64 v[250:251], 6, v[250:251]
	v_lshl_add_u64 v[250:251], s[38:39], 0, v[250:251]
	v_and_b32_e32 v248, 24, v30
	v_lshlrev_b32_e32 v248, 1, v248
	v_lshl_add_u64 v[252:253], v[250:251], 0, v[248:249]
	global_load_dwordx4 v[240:243], v[252:253], off
	s_waitcnt vmcnt(4)
	v_max3_f32 v2, v6, v8, v0
	v_sub_f32_e32 v3, v6, v2
	v_mul_f32_e32 v3, 0x3fb8aa3b, v3
	v_sub_f32_e32 v4, v8, v2
	v_exp_f32_e32 v6, v3
	v_mul_f32_e32 v4, 0x3fb8aa3b, v4
	v_sub_f32_e32 v0, v0, v2
	v_exp_f32_e32 v11, v4
	v_mul_f32_e32 v0, 0x3fb8aa3b, v0
	v_exp_f32_e32 v33, v0
	v_add_f32_e32 v3, 0, v6
	v_add_f32_e32 v3, v11, v3
	v_add_f32_e32 v0, v33, v3
	v_div_scale_f32 v2, s[6:7], v0, v0, 1.0
	v_rcp_f32_e32 v3, v2
	s_nop 0
	v_fma_f32 v4, -v2, v3, 1.0
	v_fmac_f32_e32 v3, v4, v3
	v_div_scale_f32 v4, vcc, 1.0, v0, 1.0
	v_mul_f32_e32 v5, v4, v3
	v_fma_f32 v8, -v2, v5, v4
	v_fmac_f32_e32 v5, v8, v3
	v_fma_f32 v2, -v2, v5, v4
	v_div_fmas_f32 v2, v2, v3, v5
	v_div_fixup_f32 v35, v2, v0, 1.0
	v_lshlrev_b32_e32 v0, 11, v7
	v_lshlrev_b64 v[2:3], 11, v[38:39]
	v_mul_f32_e32 v32, v6, v35
	v_lshl_add_u64 v[6:7], v[26:27], 0, v[0:1]
	v_lshlrev_b32_e32 v0, 11, v10
	v_lshl_add_u64 v[38:39], v[38:39], 0, v[16:17]
	v_mul_f32_e32 v34, v11, v35
	v_lshl_add_u64 v[10:11], v[28:29], 0, v[0:1]
	v_and_b32_e32 v0, 24, v30
	v_lshlrev_b64 v[38:39], 6, v[38:39]
	v_lshl_add_u64 v[2:3], v[24:25], 0, v[2:3]
	v_lshl_add_u64 v[38:39], s[38:39], 0, v[38:39]
	v_lshlrev_b32_e32 v0, 1, v0
	s_waitcnt vmcnt(0)
; DI unsigned pack2(float a, float b) { f32x2 v = {a, b}; bf16x2_t r = __builtin_convertvector(v, bf16x2_t); return __builtin_bit_cast(unsigned, r); }
; DI float bflo(unsigned v) { return __uint_as_float(v << 16); }
; DI float bfhi(unsigned v) { return __uint_as_float(v & 0xffff0000u); }
; DI size_t blk(size_t row, int k, int R) { return ((size_t)(k >> 5) * R + row) * 32 + (k & 31); }
; DI float silu_f(float x) { return x / (1.f + __expf(-x)); }
; DI void dil_merge_phase(const Params& p, bool probe = false) {
;     ...
;     float acc[8] = {0.f, 0.f, 0.f, 0.f, 0.f, 0.f, 0.f, 0.f};
; #pragma unroll
;     for (int gi = 0; gi < 3; ++gi) {
;       const u32x4 ov = *(const u32x4*)(p.Q + (size_t)gi * NTOK * 1024 + rows[gi] * 1024 + c * 8);
;       const float wq = wg[gi] * inv;
; #pragma unroll
;       for (int e = 0; e < 4; ++e) { acc[2 * e] += wq * bflo(ov[e]); acc[2 * e + 1] += wq * bfhi(ov[e]); }
;     }
;     bf16_t* gp = p.G + blk(t, c * 8, NTOK);
;     const u32x4 gv = *(const u32x4*)gp;
;     u32x4 ov;
; #pragma unroll
;     for (int e = 0; e < 4; ++e) ov[e] = pack2(acc[2 * e] * silu_f(bflo(gv[e])), acc[2 * e + 1] * silu_f(bfhi(gv[e])));
;     *(u32x4*)gp = ov;
;   }
	v_mov_b32_e32 v2, v232
	v_mov_b32_e32 v3, v233
	v_mov_b32_e32 v4, v234
	v_mov_b32_e32 v5, v235
	v_lshl_add_u64 v[42:43], v[38:39], 0, v[0:1]
	v_mov_b32_e32 v6, v236
	v_mov_b32_e32 v7, v237
	v_mov_b32_e32 v8, v238
	v_mov_b32_e32 v9, v239
	v_mul_f32_e32 v36, v33, v35
	v_mov_b32_e32 v38, v240
	v_mov_b32_e32 v39, v241
	v_mov_b32_e32 v40, v242
	v_mov_b32_e32 v41, v243
	v_lshl_add_u64 v[30:31], v[30:31], 0, s[8:9]
	v_mov_b32_e32 v10, v244
	v_mov_b32_e32 v11, v245
	v_mov_b32_e32 v12, v246
	v_mov_b32_e32 v13, v247
	v_lshlrev_b32_e32 v44, 16, v2
	v_and_b32_e32 v45, 0xffff0000, v2
	v_pk_fma_f32 v[44:45], v[32:33], v[44:45], 0 op_sel_hi:[0,1,0]
	v_lshlrev_b32_e32 v46, 16, v6
	v_and_b32_e32 v47, 0xffff0000, v6
	v_lshlrev_b32_e32 v0, 16, v38
	v_pk_fma_f32 v[44:45], v[34:35], v[46:47], v[44:45] op_sel_hi:[0,1,1]
	v_lshlrev_b32_e32 v46, 16, v10
	v_and_b32_e32 v47, 0xffff0000, v10
	v_and_b32_e32 v2, 0xffff0000, v38
	v_mul_f32_e32 v6, 0xbfb8aa3b, v0
	v_pk_fma_f32 v[44:45], v[36:37], v[46:47], v[44:45] op_sel_hi:[0,1,1]
	v_exp_f32_e32 v46, v6
	v_mul_f32_e32 v6, 0xbfb8aa3b, v2
	v_exp_f32_e32 v47, v6
	s_nop 0
	v_pk_add_f32 v[46:47], v[46:47], 1.0 op_sel_hi:[1,0]
	s_nop 0
	v_div_scale_f32 v6, s[6:7], v47, v47, v2
	v_rcp_f32_e32 v10, v6
	s_nop 0
	v_fma_f32 v33, -v6, v10, 1.0
	v_fmac_f32_e32 v10, v33, v10
	v_div_scale_f32 v33, vcc, v2, v47, v2
	v_mul_f32_e32 v35, v33, v10
	v_fma_f32 v37, -v6, v35, v33
	v_fmac_f32_e32 v35, v37, v10
	v_fma_f32 v6, -v6, v35, v33
	v_div_fmas_f32 v6, v6, v10, v35
	v_div_fixup_f32 v47, v6, v47, v2
	v_div_scale_f32 v2, s[6:7], v46, v46, v0
	v_rcp_f32_e32 v6, v2
	s_nop 0
	v_fma_f32 v10, -v2, v6, 1.0
	v_fmac_f32_e32 v6, v10, v6
	v_div_scale_f32 v10, vcc, v0, v46, v0
	v_mul_f32_e32 v33, v10, v6
	v_fma_f32 v35, -v2, v33, v10
	v_fmac_f32_e32 v33, v35, v6
	v_fma_f32 v2, -v2, v33, v10
	v_div_fmas_f32 v2, v2, v6, v33
	v_div_fixup_f32 v46, v2, v46, v0
	v_pk_mul_f32 v[44:45], v[46:47], v[44:45]
	v_lshlrev_b32_e32 v6, 16, v7
	v_cvt_pk_bf16_f32 v2, v44, v45
	v_lshlrev_b32_e32 v44, 16, v3
	v_and_b32_e32 v45, 0xffff0000, v3
	v_pk_fma_f32 v[44:45], v[32:33], v[44:45], 0 op_sel_hi:[0,1,0]
	v_and_b32_e32 v7, 0xffff0000, v7
	v_pk_fma_f32 v[6:7], v[34:35], v[6:7], v[44:45] op_sel_hi:[0,1,1]
	v_lshlrev_b32_e32 v10, 16, v11
	v_and_b32_e32 v11, 0xffff0000, v11
	v_lshlrev_b32_e32 v0, 16, v39
	v_and_b32_e32 v3, 0xffff0000, v39
	v_pk_fma_f32 v[6:7], v[36:37], v[10:11], v[6:7] op_sel_hi:[0,1,1]
	v_mul_f32_e32 v10, 0xbfb8aa3b, v0
	v_mul_f32_e32 v11, 0xbfb8aa3b, v3
	v_exp_f32_e32 v10, v10
	v_exp_f32_e32 v11, v11
	s_nop 0
	v_pk_add_f32 v[10:11], v[10:11], 1.0 op_sel_hi:[1,0]
	s_nop 0
	v_div_scale_f32 v33, s[6:7], v11, v11, v3
	v_rcp_f32_e32 v35, v33
	s_nop 0
	v_fma_f32 v37, -v33, v35, 1.0
	v_fmac_f32_e32 v35, v37, v35
	v_div_scale_f32 v37, vcc, v3, v11, v3
	v_mul_f32_e32 v38, v37, v35
	v_fma_f32 v39, -v33, v38, v37
	v_fmac_f32_e32 v38, v39, v35
	v_fma_f32 v33, -v33, v38, v37
	v_div_fmas_f32 v33, v33, v35, v38
	v_div_fixup_f32 v11, v33, v11, v3
	v_div_scale_f32 v3, s[6:7], v10, v10, v0
	v_rcp_f32_e32 v33, v3
	s_nop 0
	v_fma_f32 v35, -v3, v33, 1.0
	v_fmac_f32_e32 v33, v35, v33
	v_div_scale_f32 v35, vcc, v0, v10, v0
	v_mul_f32_e32 v37, v35, v33
	v_fma_f32 v38, -v3, v37, v35
	v_fmac_f32_e32 v37, v38, v33
	v_fma_f32 v3, -v3, v37, v35
	v_div_fmas_f32 v3, v3, v33, v37
	v_div_fixup_f32 v10, v3, v10, v0
	v_pk_mul_f32 v[6:7], v[10:11], v[6:7]
	v_lshlrev_b32_e32 v10, 16, v8
	v_cvt_pk_bf16_f32 v3, v6, v7
	v_lshlrev_b32_e32 v6, 16, v4
	v_and_b32_e32 v7, 0xffff0000, v4
	v_pk_fma_f32 v[6:7], v[32:33], v[6:7], 0 op_sel_hi:[0,1,0]
	v_and_b32_e32 v11, 0xffff0000, v8
	v_lshlrev_b32_e32 v0, 16, v40
	v_pk_fma_f32 v[6:7], v[34:35], v[10:11], v[6:7] op_sel_hi:[0,1,1]
	v_lshlrev_b32_e32 v10, 16, v12
	v_and_b32_e32 v11, 0xffff0000, v12
	v_and_b32_e32 v4, 0xffff0000, v40
	v_mul_f32_e32 v8, 0xbfb8aa3b, v0
	v_pk_fma_f32 v[6:7], v[36:37], v[10:11], v[6:7] op_sel_hi:[0,1,1]
	v_exp_f32_e32 v10, v8
	v_mul_f32_e32 v8, 0xbfb8aa3b, v4
	v_exp_f32_e32 v11, v8
	s_nop 0
	v_pk_add_f32 v[10:11], v[10:11], 1.0 op_sel_hi:[1,0]
	s_nop 0
	v_div_scale_f32 v8, s[6:7], v11, v11, v4
	v_rcp_f32_e32 v12, v8
	s_nop 0
	v_fma_f32 v33, -v8, v12, 1.0
	v_fmac_f32_e32 v12, v33, v12
	v_div_scale_f32 v33, vcc, v4, v11, v4
	v_mul_f32_e32 v35, v33, v12
	v_fma_f32 v37, -v8, v35, v33
	v_fmac_f32_e32 v35, v37, v12
	v_fma_f32 v8, -v8, v35, v33
	v_div_fmas_f32 v8, v8, v12, v35
	v_div_fixup_f32 v11, v8, v11, v4
	v_div_scale_f32 v4, s[6:7], v10, v10, v0
	v_rcp_f32_e32 v8, v4
	s_nop 0
	v_fma_f32 v12, -v4, v8, 1.0
	v_fmac_f32_e32 v8, v12, v8
	v_div_scale_f32 v12, vcc, v0, v10, v0
	v_mul_f32_e32 v33, v12, v8
	v_fma_f32 v35, -v4, v33, v12
	v_fmac_f32_e32 v33, v35, v8
	v_fma_f32 v4, -v4, v33, v12
	v_div_fmas_f32 v4, v4, v8, v33
	v_div_fixup_f32 v10, v4, v10, v0
	v_pk_mul_f32 v[6:7], v[10:11], v[6:7]
	v_lshlrev_b32_e32 v8, 16, v9
	v_cvt_pk_bf16_f32 v4, v6, v7
	v_lshlrev_b32_e32 v6, 16, v5
	v_and_b32_e32 v7, 0xffff0000, v5
	v_pk_fma_f32 v[6:7], v[32:33], v[6:7], 0 op_sel_hi:[0,1,0]
	v_and_b32_e32 v9, 0xffff0000, v9
	v_pk_fma_f32 v[6:7], v[34:35], v[8:9], v[6:7] op_sel_hi:[0,1,1]
	v_lshlrev_b32_e32 v8, 16, v13
	v_and_b32_e32 v9, 0xffff0000, v13
	v_lshlrev_b32_e32 v0, 16, v41
	v_and_b32_e32 v5, 0xffff0000, v41
	v_pk_fma_f32 v[6:7], v[36:37], v[8:9], v[6:7] op_sel_hi:[0,1,1]
	v_mul_f32_e32 v8, 0xbfb8aa3b, v0
	v_mul_f32_e32 v9, 0xbfb8aa3b, v5
	v_exp_f32_e32 v8, v8
	v_exp_f32_e32 v9, v9
	s_nop 0
	v_pk_add_f32 v[8:9], v[8:9], 1.0 op_sel_hi:[1,0]
	s_nop 0
	v_div_scale_f32 v10, s[6:7], v9, v9, v5
	v_rcp_f32_e32 v11, v10
	s_nop 0
	v_fma_f32 v12, -v10, v11, 1.0
	v_fmac_f32_e32 v11, v12, v11
	v_div_scale_f32 v12, vcc, v5, v9, v5
	v_mul_f32_e32 v13, v12, v11
	v_fma_f32 v32, -v10, v13, v12
	v_fmac_f32_e32 v13, v32, v11
	v_fma_f32 v10, -v10, v13, v12
	v_div_fmas_f32 v10, v10, v11, v13
	v_div_fixup_f32 v9, v10, v9, v5
	v_div_scale_f32 v5, s[6:7], v8, v8, v0
	v_rcp_f32_e32 v10, v5
	s_mov_b64 s[6:7], 0x3fffff
	v_fma_f32 v11, -v5, v10, 1.0
	v_fmac_f32_e32 v10, v11, v10
	v_div_scale_f32 v11, vcc, v0, v8, v0
	v_mul_f32_e32 v12, v11, v10
	v_fma_f32 v13, -v5, v12, v11
	v_fmac_f32_e32 v12, v13, v10
	v_fma_f32 v5, -v5, v12, v11
	v_div_fmas_f32 v5, v5, v10, v12
	v_div_fixup_f32 v8, v5, v8, v0
	v_pk_mul_f32 v[6:7], v[8:9], v[6:7]
	v_cmp_lt_u64_e32 vcc, s[6:7], v[14:15]
	v_cvt_pk_bf16_f32 v5, v6, v7
	s_or_b64 s[4:5], vcc, s[4:5]
	global_store_dwordx4 v[42:43], v[2:5], off
	s_andn2_b64 exec, exec, s[4:5]
	s_cbranch_execnz .LBB0_865

; __global__ void __launch_bounds__(256, 2) mega_kernel(Params p) {
	.amdhsa_kernel _Z11mega_kernel6Params
		.amdhsa_group_segment_fixed_size 0
		.amdhsa_private_segment_fixed_size 0
		.amdhsa_kernarg_size 2784
		.amdhsa_user_sgpr_count 2
		.amdhsa_user_sgpr_dispatch_ptr 0
		.amdhsa_user_sgpr_queue_ptr 0
		.amdhsa_user_sgpr_kernarg_segment_ptr 1
		.amdhsa_user_sgpr_dispatch_id 0
		.amdhsa_user_sgpr_kernarg_preload_length 0
		.amdhsa_user_sgpr_kernarg_preload_offset 0
		.amdhsa_user_sgpr_private_segment_size 0
		.amdhsa_uses_dynamic_stack 0
		.amdhsa_enable_private_segment 0
		.amdhsa_system_sgpr_workgroup_id_x 1
		.amdhsa_system_sgpr_workgroup_id_y 0
		.amdhsa_system_sgpr_workgroup_id_z 0
		.amdhsa_system_sgpr_workgroup_info 0
		.amdhsa_system_vgpr_workitem_id 2
		.amdhsa_next_free_vgpr 256
		.amdhsa_next_free_sgpr 102
		.amdhsa_accum_offset 256
		.amdhsa_reserve_vcc 1
		.amdhsa_float_round_mode_32 0
		.amdhsa_float_round_mode_16_64 0
		.amdhsa_float_denorm_mode_32 3
		.amdhsa_float_denorm_mode_16_64 3
		.amdhsa_dx10_clamp 1
		.amdhsa_ieee_mode 1
		.amdhsa_fp16_overflow 0
		.amdhsa_tg_split 0
		.amdhsa_exception_fp_ieee_invalid_op 0
		.amdhsa_exception_fp_denorm_src 0
		.amdhsa_exception_fp_ieee_div_zero 0
		.amdhsa_exception_fp_ieee_overflow 0
		.amdhsa_exception_fp_ieee_underflow 0
		.amdhsa_exception_fp_ieee_inexact 0
		.amdhsa_exception_int_div_zero 0
	.end_amdhsa_kernel

; __global__ void __launch_bounds__(256, 2) mega_kernel(Params p) {
amdhsa.kernels:
  - .agpr_count:     0
    .args:
      - .offset:         0
        .size:           2528
        .value_kind:     by_value
      - .offset:         2528
        .size:           4
        .value_kind:     hidden_block_count_x
      - .offset:         2532
        .size:           4
        .value_kind:     hidden_block_count_y
      - .offset:         2536
        .size:           4
        .value_kind:     hidden_block_count_z
      - .offset:         2540
        .size:           2
        .value_kind:     hidden_group_size_x
      - .offset:         2542
        .size:           2
        .value_kind:     hidden_group_size_y
      - .offset:         2544
        .size:           2
        .value_kind:     hidden_group_size_z
      - .offset:         2546
        .size:           2
        .value_kind:     hidden_remainder_x
      - .offset:         2548
        .size:           2
        .value_kind:     hidden_remainder_y
      - .offset:         2550
        .size:           2
        .value_kind:     hidden_remainder_z
      - .offset:         2568
        .size:           8
        .value_kind:     hidden_global_offset_x
      - .offset:         2576
        .size:           8
        .value_kind:     hidden_global_offset_y
      - .offset:         2584
        .size:           8
        .value_kind:     hidden_global_offset_z
      - .offset:         2592
        .size:           2
        .value_kind:     hidden_grid_dims
      - .offset:         2616
        .size:           8
        .value_kind:     hidden_multigrid_sync_arg
      - .offset:         2648
        .size:           4
        .value_kind:     hidden_dynamic_lds_size
    .group_segment_fixed_size: 0
    .kernarg_segment_align: 8
    .kernarg_segment_size: 2784
    .language:       OpenCL C
    .language_version:
      - 2
      - 0
    .max_flat_workgroup_size: 256
    .name:           _Z11mega_kernel6Params
    .private_segment_fixed_size: 0
    .sgpr_count:     108
    .sgpr_spill_count: 128
    .symbol:         _Z11mega_kernel6Params.kd
    .uniform_work_group_size: 1
    .uses_dynamic_stack: false
    .vgpr_count:     256
    .vgpr_spill_count: 0
    .wavefront_size: 64
